# v65 + fused P7 scale step software-pipelined: the second accumulator half's gate loads are issued as each row group of the first half is consumed
# baseline (speedup 1.0000x reference)
.Lp7_scale:
	v_lshl_add_u32 v146, s36, 8, v151
	v_lshl_add_u32 v144, s61, 8, v153
	v_ashrrev_i32_e32 v145, 31, v144
	v_lshlrev_b64 v[144:145], 1, v[144:145]
	v_add_u32_e32 v148, 0x0, v146
	v_ashrrev_i32_e32 v149, 31, v148
	v_lshlrev_b64 v[148:149], 12, v[148:149]
	v_lshl_add_u64 v[148:149], s[20:21], 0, v[148:149]
	v_lshl_add_u64 v[148:149], v[148:149], 0, v[144:145]
	global_load_dwordx4 v[156:159], v[148:149], off
	global_load_dwordx4 v[160:163], v[148:149], off offset:256
	global_load_dwordx4 v[192:195], v[148:149], off offset:2048
	global_load_dwordx4 v[196:199], v[148:149], off offset:2304
	v_add_u32_e32 v148, 0x10, v146
	v_ashrrev_i32_e32 v149, 31, v148
	v_lshlrev_b64 v[148:149], 12, v[148:149]
	v_lshl_add_u64 v[148:149], s[20:21], 0, v[148:149]
	v_lshl_add_u64 v[148:149], v[148:149], 0, v[144:145]
	global_load_dwordx4 v[164:167], v[148:149], off
	global_load_dwordx4 v[168:171], v[148:149], off offset:256
	global_load_dwordx4 v[200:203], v[148:149], off offset:2048
	global_load_dwordx4 v[204:207], v[148:149], off offset:2304
	v_add_u32_e32 v148, 0x20, v146
	v_ashrrev_i32_e32 v149, 31, v148
	v_lshlrev_b64 v[148:149], 12, v[148:149]
	v_lshl_add_u64 v[148:149], s[20:21], 0, v[148:149]
	v_lshl_add_u64 v[148:149], v[148:149], 0, v[144:145]
	global_load_dwordx4 v[172:175], v[148:149], off
	global_load_dwordx4 v[176:179], v[148:149], off offset:256
	global_load_dwordx4 v[208:211], v[148:149], off offset:2048
	global_load_dwordx4 v[212:215], v[148:149], off offset:2304
	v_add_u32_e32 v148, 0x30, v146
	v_ashrrev_i32_e32 v149, 31, v148
	v_lshlrev_b64 v[148:149], 12, v[148:149]
	v_lshl_add_u64 v[148:149], s[20:21], 0, v[148:149]
	v_lshl_add_u64 v[148:149], v[148:149], 0, v[144:145]
	global_load_dwordx4 v[180:183], v[148:149], off
	global_load_dwordx4 v[188:191], v[148:149], off offset:256
	global_load_dwordx4 v[216:219], v[148:149], off offset:2048
	global_load_dwordx4 v[220:223], v[148:149], off offset:2304
	s_waitcnt vmcnt(12)
	v_lshlrev_b32_e32 v224, 16, v192
	v_and_b32_e32 v225, 0xffff0000, v192
	v_lshlrev_b32_e32 v226, 16, v193
	v_and_b32_e32 v227, 0xffff0000, v193
	v_lshlrev_b32_e32 v228, 16, v194
	v_and_b32_e32 v229, 0xffff0000, v194
	v_lshlrev_b32_e32 v230, 16, v195
	v_and_b32_e32 v231, 0xffff0000, v195
	v_max_f32_e32 v224, 0x21800000, v224
	v_max_f32_e32 v225, 0x21800000, v225
	v_max_f32_e32 v226, 0x21800000, v226
	v_max_f32_e32 v227, 0x21800000, v227
	v_max_f32_e32 v228, 0x21800000, v228
	v_max_f32_e32 v229, 0x21800000, v229
	v_max_f32_e32 v230, 0x21800000, v230
	v_max_f32_e32 v231, 0x21800000, v231
	v_rcp_f32_e32 v224, v224
	v_rcp_f32_e32 v225, v225
	v_rcp_f32_e32 v226, v226
	v_rcp_f32_e32 v227, v227
	v_rcp_f32_e32 v228, v228
	v_rcp_f32_e32 v229, v229
	v_rcp_f32_e32 v230, v230
	v_rcp_f32_e32 v231, v231
	v_lshlrev_b32_e32 v232, 16, v156
	v_and_b32_e32 v233, 0xffff0000, v156
	v_lshlrev_b32_e32 v234, 16, v157
	v_and_b32_e32 v235, 0xffff0000, v157
	v_lshlrev_b32_e32 v236, 16, v158
	v_and_b32_e32 v237, 0xffff0000, v158
	v_lshlrev_b32_e32 v238, 16, v159
	v_and_b32_e32 v239, 0xffff0000, v159
	v_pk_mul_f32 v[232:233], v[232:233], v[224:225]
	v_pk_mul_f32 v[234:235], v[234:235], v[226:227]
	v_pk_mul_f32 v[236:237], v[236:237], v[228:229]
	v_pk_mul_f32 v[238:239], v[238:239], v[230:231]
	v_pk_mul_f32 v[108:109], v[108:109], v[232:233]
	v_pk_mul_f32 v[110:111], v[110:111], v[234:235]
	v_pk_mul_f32 v[112:113], v[112:113], v[236:237]
	v_pk_mul_f32 v[114:115], v[114:115], v[238:239]
	v_lshlrev_b32_e32 v224, 16, v196
	v_and_b32_e32 v225, 0xffff0000, v196
	v_lshlrev_b32_e32 v226, 16, v197
	v_and_b32_e32 v227, 0xffff0000, v197
	v_lshlrev_b32_e32 v228, 16, v198
	v_and_b32_e32 v229, 0xffff0000, v198
	v_lshlrev_b32_e32 v230, 16, v199
	v_and_b32_e32 v231, 0xffff0000, v199
	v_max_f32_e32 v224, 0x21800000, v224
	v_max_f32_e32 v225, 0x21800000, v225
	v_max_f32_e32 v226, 0x21800000, v226
	v_max_f32_e32 v227, 0x21800000, v227
	v_max_f32_e32 v228, 0x21800000, v228
	v_max_f32_e32 v229, 0x21800000, v229
	v_max_f32_e32 v230, 0x21800000, v230
	v_max_f32_e32 v231, 0x21800000, v231
	v_rcp_f32_e32 v224, v224
	v_rcp_f32_e32 v225, v225
	v_rcp_f32_e32 v226, v226
	v_rcp_f32_e32 v227, v227
	v_rcp_f32_e32 v228, v228
	v_rcp_f32_e32 v229, v229
	v_rcp_f32_e32 v230, v230
	v_rcp_f32_e32 v231, v231
	v_lshlrev_b32_e32 v232, 16, v160
	v_and_b32_e32 v233, 0xffff0000, v160
	v_lshlrev_b32_e32 v234, 16, v161
	v_and_b32_e32 v235, 0xffff0000, v161
	v_lshlrev_b32_e32 v236, 16, v162
	v_and_b32_e32 v237, 0xffff0000, v162
	v_lshlrev_b32_e32 v238, 16, v163
	v_and_b32_e32 v239, 0xffff0000, v163
	v_pk_mul_f32 v[232:233], v[232:233], v[224:225]
	v_pk_mul_f32 v[234:235], v[234:235], v[226:227]
	v_pk_mul_f32 v[236:237], v[236:237], v[228:229]
	v_pk_mul_f32 v[238:239], v[238:239], v[230:231]
	v_pk_mul_f32 v[120:121], v[120:121], v[232:233]
	v_pk_mul_f32 v[122:123], v[122:123], v[234:235]
	v_pk_mul_f32 v[124:125], v[124:125], v[236:237]
	v_pk_mul_f32 v[126:127], v[126:127], v[238:239]
	v_add_u32_e32 v148, 0x80, v146
	v_ashrrev_i32_e32 v149, 31, v148
	v_lshlrev_b64 v[148:149], 12, v[148:149]
	v_lshl_add_u64 v[148:149], s[20:21], 0, v[148:149]
	v_lshl_add_u64 v[148:149], v[148:149], 0, v[144:145]
	global_load_dwordx4 v[156:159], v[148:149], off
	global_load_dwordx4 v[160:163], v[148:149], off offset:256
	global_load_dwordx4 v[192:195], v[148:149], off offset:2048
	global_load_dwordx4 v[196:199], v[148:149], off offset:2304
	s_waitcnt vmcnt(12)
	v_lshlrev_b32_e32 v224, 16, v200
	v_and_b32_e32 v225, 0xffff0000, v200
	v_lshlrev_b32_e32 v226, 16, v201
	v_and_b32_e32 v227, 0xffff0000, v201
	v_lshlrev_b32_e32 v228, 16, v202
	v_and_b32_e32 v229, 0xffff0000, v202
	v_lshlrev_b32_e32 v230, 16, v203
	v_and_b32_e32 v231, 0xffff0000, v203
	v_max_f32_e32 v224, 0x21800000, v224
	v_max_f32_e32 v225, 0x21800000, v225
	v_max_f32_e32 v226, 0x21800000, v226
	v_max_f32_e32 v227, 0x21800000, v227
	v_max_f32_e32 v228, 0x21800000, v228
	v_max_f32_e32 v229, 0x21800000, v229
	v_max_f32_e32 v230, 0x21800000, v230
	v_max_f32_e32 v231, 0x21800000, v231
	v_rcp_f32_e32 v224, v224
	v_rcp_f32_e32 v225, v225
	v_rcp_f32_e32 v226, v226
	v_rcp_f32_e32 v227, v227
	v_rcp_f32_e32 v228, v228
	v_rcp_f32_e32 v229, v229
	v_rcp_f32_e32 v230, v230
	v_rcp_f32_e32 v231, v231
	v_lshlrev_b32_e32 v232, 16, v164
	v_and_b32_e32 v233, 0xffff0000, v164
	v_lshlrev_b32_e32 v234, 16, v165
	v_and_b32_e32 v235, 0xffff0000, v165
	v_lshlrev_b32_e32 v236, 16, v166
	v_and_b32_e32 v237, 0xffff0000, v166
	v_lshlrev_b32_e32 v238, 16, v167
	v_and_b32_e32 v239, 0xffff0000, v167
	v_pk_mul_f32 v[232:233], v[232:233], v[224:225]
	v_pk_mul_f32 v[234:235], v[234:235], v[226:227]
	v_pk_mul_f32 v[236:237], v[236:237], v[228:229]
	v_pk_mul_f32 v[238:239], v[238:239], v[230:231]
	v_pk_mul_f32 v[96:97], v[96:97], v[232:233]
	v_pk_mul_f32 v[98:99], v[98:99], v[234:235]
	v_pk_mul_f32 v[100:101], v[100:101], v[236:237]
	v_pk_mul_f32 v[102:103], v[102:103], v[238:239]
	v_lshlrev_b32_e32 v224, 16, v204
	v_and_b32_e32 v225, 0xffff0000, v204
	v_lshlrev_b32_e32 v226, 16, v205
	v_and_b32_e32 v227, 0xffff0000, v205
	v_lshlrev_b32_e32 v228, 16, v206
	v_and_b32_e32 v229, 0xffff0000, v206
	v_lshlrev_b32_e32 v230, 16, v207
	v_and_b32_e32 v231, 0xffff0000, v207
	v_max_f32_e32 v224, 0x21800000, v224
	v_max_f32_e32 v225, 0x21800000, v225
	v_max_f32_e32 v226, 0x21800000, v226
	v_max_f32_e32 v227, 0x21800000, v227
	v_max_f32_e32 v228, 0x21800000, v228
	v_max_f32_e32 v229, 0x21800000, v229
	v_max_f32_e32 v230, 0x21800000, v230
	v_max_f32_e32 v231, 0x21800000, v231
	v_rcp_f32_e32 v224, v224
	v_rcp_f32_e32 v225, v225
	v_rcp_f32_e32 v226, v226
	v_rcp_f32_e32 v227, v227
	v_rcp_f32_e32 v228, v228
	v_rcp_f32_e32 v229, v229
	v_rcp_f32_e32 v230, v230
	v_rcp_f32_e32 v231, v231
	v_lshlrev_b32_e32 v232, 16, v168
	v_and_b32_e32 v233, 0xffff0000, v168
	v_lshlrev_b32_e32 v234, 16, v169
	v_and_b32_e32 v235, 0xffff0000, v169
	v_lshlrev_b32_e32 v236, 16, v170
	v_and_b32_e32 v237, 0xffff0000, v170
	v_lshlrev_b32_e32 v238, 16, v171
	v_and_b32_e32 v239, 0xffff0000, v171
	v_pk_mul_f32 v[232:233], v[232:233], v[224:225]
	v_pk_mul_f32 v[234:235], v[234:235], v[226:227]
	v_pk_mul_f32 v[236:237], v[236:237], v[228:229]
	v_pk_mul_f32 v[238:239], v[238:239], v[230:231]
	v_pk_mul_f32 v[116:117], v[116:117], v[232:233]
	v_pk_mul_f32 v[118:119], v[118:119], v[234:235]
	v_pk_mul_f32 v[104:105], v[104:105], v[236:237]
	v_pk_mul_f32 v[106:107], v[106:107], v[238:239]
	v_add_u32_e32 v148, 0x90, v146
	v_ashrrev_i32_e32 v149, 31, v148
	v_lshlrev_b64 v[148:149], 12, v[148:149]
	v_lshl_add_u64 v[148:149], s[20:21], 0, v[148:149]
	v_lshl_add_u64 v[148:149], v[148:149], 0, v[144:145]
	global_load_dwordx4 v[164:167], v[148:149], off
	global_load_dwordx4 v[168:171], v[148:149], off offset:256
	global_load_dwordx4 v[200:203], v[148:149], off offset:2048
	global_load_dwordx4 v[204:207], v[148:149], off offset:2304
	s_waitcnt vmcnt(12)
	v_lshlrev_b32_e32 v224, 16, v208
	v_and_b32_e32 v225, 0xffff0000, v208
	v_lshlrev_b32_e32 v226, 16, v209
	v_and_b32_e32 v227, 0xffff0000, v209
	v_lshlrev_b32_e32 v228, 16, v210
	v_and_b32_e32 v229, 0xffff0000, v210
	v_lshlrev_b32_e32 v230, 16, v211
	v_and_b32_e32 v231, 0xffff0000, v211
	v_max_f32_e32 v224, 0x21800000, v224
	v_max_f32_e32 v225, 0x21800000, v225
	v_max_f32_e32 v226, 0x21800000, v226
	v_max_f32_e32 v227, 0x21800000, v227
	v_max_f32_e32 v228, 0x21800000, v228
	v_max_f32_e32 v229, 0x21800000, v229
	v_max_f32_e32 v230, 0x21800000, v230
	v_max_f32_e32 v231, 0x21800000, v231
	v_rcp_f32_e32 v224, v224
	v_rcp_f32_e32 v225, v225
	v_rcp_f32_e32 v226, v226
	v_rcp_f32_e32 v227, v227
	v_rcp_f32_e32 v228, v228
	v_rcp_f32_e32 v229, v229
	v_rcp_f32_e32 v230, v230
	v_rcp_f32_e32 v231, v231
	v_lshlrev_b32_e32 v232, 16, v172
	v_and_b32_e32 v233, 0xffff0000, v172
	v_lshlrev_b32_e32 v234, 16, v173
	v_and_b32_e32 v235, 0xffff0000, v173
	v_lshlrev_b32_e32 v236, 16, v174
	v_and_b32_e32 v237, 0xffff0000, v174
	v_lshlrev_b32_e32 v238, 16, v175
	v_and_b32_e32 v239, 0xffff0000, v175
	v_pk_mul_f32 v[232:233], v[232:233], v[224:225]
	v_pk_mul_f32 v[234:235], v[234:235], v[226:227]
	v_pk_mul_f32 v[236:237], v[236:237], v[228:229]
	v_pk_mul_f32 v[238:239], v[238:239], v[230:231]
	v_pk_mul_f32 v[92:93], v[92:93], v[232:233]
	v_pk_mul_f32 v[94:95], v[94:95], v[234:235]
	v_pk_mul_f32 v[84:85], v[84:85], v[236:237]
	v_pk_mul_f32 v[86:87], v[86:87], v[238:239]
	v_lshlrev_b32_e32 v224, 16, v212
	v_and_b32_e32 v225, 0xffff0000, v212
	v_lshlrev_b32_e32 v226, 16, v213
	v_and_b32_e32 v227, 0xffff0000, v213
	v_lshlrev_b32_e32 v228, 16, v214
	v_and_b32_e32 v229, 0xffff0000, v214
	v_lshlrev_b32_e32 v230, 16, v215
	v_and_b32_e32 v231, 0xffff0000, v215
	v_max_f32_e32 v224, 0x21800000, v224
	v_max_f32_e32 v225, 0x21800000, v225
	v_max_f32_e32 v226, 0x21800000, v226
	v_max_f32_e32 v227, 0x21800000, v227
	v_max_f32_e32 v228, 0x21800000, v228
	v_max_f32_e32 v229, 0x21800000, v229
	v_max_f32_e32 v230, 0x21800000, v230
	v_max_f32_e32 v231, 0x21800000, v231
	v_rcp_f32_e32 v224, v224
	v_rcp_f32_e32 v225, v225
	v_rcp_f32_e32 v226, v226
	v_rcp_f32_e32 v227, v227
	v_rcp_f32_e32 v228, v228
	v_rcp_f32_e32 v229, v229
	v_rcp_f32_e32 v230, v230
	v_rcp_f32_e32 v231, v231
	v_lshlrev_b32_e32 v232, 16, v176
	v_and_b32_e32 v233, 0xffff0000, v176
	v_lshlrev_b32_e32 v234, 16, v177
	v_and_b32_e32 v235, 0xffff0000, v177
	v_lshlrev_b32_e32 v236, 16, v178
	v_and_b32_e32 v237, 0xffff0000, v178
	v_lshlrev_b32_e32 v238, 16, v179
	v_and_b32_e32 v239, 0xffff0000, v179
	v_pk_mul_f32 v[232:233], v[232:233], v[224:225]
	v_pk_mul_f32 v[234:235], v[234:235], v[226:227]
	v_pk_mul_f32 v[236:237], v[236:237], v[228:229]
	v_pk_mul_f32 v[238:239], v[238:239], v[230:231]
	v_pk_mul_f32 v[88:89], v[88:89], v[232:233]
	v_pk_mul_f32 v[90:91], v[90:91], v[234:235]
	v_pk_mul_f32 v[80:81], v[80:81], v[236:237]
	v_pk_mul_f32 v[82:83], v[82:83], v[238:239]
	v_add_u32_e32 v148, 0xa0, v146
	v_ashrrev_i32_e32 v149, 31, v148
	v_lshlrev_b64 v[148:149], 12, v[148:149]
	v_lshl_add_u64 v[148:149], s[20:21], 0, v[148:149]
	v_lshl_add_u64 v[148:149], v[148:149], 0, v[144:145]
	global_load_dwordx4 v[172:175], v[148:149], off
	global_load_dwordx4 v[176:179], v[148:149], off offset:256
	global_load_dwordx4 v[208:211], v[148:149], off offset:2048
	global_load_dwordx4 v[212:215], v[148:149], off offset:2304
	s_waitcnt vmcnt(12)
	v_lshlrev_b32_e32 v224, 16, v216
	v_and_b32_e32 v225, 0xffff0000, v216
	v_lshlrev_b32_e32 v226, 16, v217
	v_and_b32_e32 v227, 0xffff0000, v217
	v_lshlrev_b32_e32 v228, 16, v218
	v_and_b32_e32 v229, 0xffff0000, v218
	v_lshlrev_b32_e32 v230, 16, v219
	v_and_b32_e32 v231, 0xffff0000, v219
	v_max_f32_e32 v224, 0x21800000, v224
	v_max_f32_e32 v225, 0x21800000, v225
	v_max_f32_e32 v226, 0x21800000, v226
	v_max_f32_e32 v227, 0x21800000, v227
	v_max_f32_e32 v228, 0x21800000, v228
	v_max_f32_e32 v229, 0x21800000, v229
	v_max_f32_e32 v230, 0x21800000, v230
	v_max_f32_e32 v231, 0x21800000, v231
	v_rcp_f32_e32 v224, v224
	v_rcp_f32_e32 v225, v225
	v_rcp_f32_e32 v226, v226
	v_rcp_f32_e32 v227, v227
	v_rcp_f32_e32 v228, v228
	v_rcp_f32_e32 v229, v229
	v_rcp_f32_e32 v230, v230
	v_rcp_f32_e32 v231, v231
	v_lshlrev_b32_e32 v232, 16, v180
	v_and_b32_e32 v233, 0xffff0000, v180
	v_lshlrev_b32_e32 v234, 16, v181
	v_and_b32_e32 v235, 0xffff0000, v181
	v_lshlrev_b32_e32 v236, 16, v182
	v_and_b32_e32 v237, 0xffff0000, v182
	v_lshlrev_b32_e32 v238, 16, v183
	v_and_b32_e32 v239, 0xffff0000, v183
	v_pk_mul_f32 v[232:233], v[232:233], v[224:225]
	v_pk_mul_f32 v[234:235], v[234:235], v[226:227]
	v_pk_mul_f32 v[236:237], v[236:237], v[228:229]
	v_pk_mul_f32 v[238:239], v[238:239], v[230:231]
	v_pk_mul_f32 v[76:77], v[76:77], v[232:233]
	v_pk_mul_f32 v[78:79], v[78:79], v[234:235]
	v_pk_mul_f32 v[68:69], v[68:69], v[236:237]
	v_pk_mul_f32 v[70:71], v[70:71], v[238:239]
	v_lshlrev_b32_e32 v224, 16, v220
	v_and_b32_e32 v225, 0xffff0000, v220
	v_lshlrev_b32_e32 v226, 16, v221
	v_and_b32_e32 v227, 0xffff0000, v221
	v_lshlrev_b32_e32 v228, 16, v222
	v_and_b32_e32 v229, 0xffff0000, v222
	v_lshlrev_b32_e32 v230, 16, v223
	v_and_b32_e32 v231, 0xffff0000, v223
	v_max_f32_e32 v224, 0x21800000, v224
	v_max_f32_e32 v225, 0x21800000, v225
	v_max_f32_e32 v226, 0x21800000, v226
	v_max_f32_e32 v227, 0x21800000, v227
	v_max_f32_e32 v228, 0x21800000, v228
	v_max_f32_e32 v229, 0x21800000, v229
	v_max_f32_e32 v230, 0x21800000, v230
	v_max_f32_e32 v231, 0x21800000, v231
	v_rcp_f32_e32 v224, v224
	v_rcp_f32_e32 v225, v225
	v_rcp_f32_e32 v226, v226
	v_rcp_f32_e32 v227, v227
	v_rcp_f32_e32 v228, v228
	v_rcp_f32_e32 v229, v229
	v_rcp_f32_e32 v230, v230
	v_rcp_f32_e32 v231, v231
	v_lshlrev_b32_e32 v232, 16, v188
	v_and_b32_e32 v233, 0xffff0000, v188
	v_lshlrev_b32_e32 v234, 16, v189
	v_and_b32_e32 v235, 0xffff0000, v189
	v_lshlrev_b32_e32 v236, 16, v190
	v_and_b32_e32 v237, 0xffff0000, v190
	v_lshlrev_b32_e32 v238, 16, v191
	v_and_b32_e32 v239, 0xffff0000, v191
	v_pk_mul_f32 v[232:233], v[232:233], v[224:225]
	v_pk_mul_f32 v[234:235], v[234:235], v[226:227]
	v_pk_mul_f32 v[236:237], v[236:237], v[228:229]
	v_pk_mul_f32 v[238:239], v[238:239], v[230:231]
	v_pk_mul_f32 v[72:73], v[72:73], v[232:233]
	v_pk_mul_f32 v[74:75], v[74:75], v[234:235]
	v_pk_mul_f32 v[64:65], v[64:65], v[236:237]
	v_pk_mul_f32 v[66:67], v[66:67], v[238:239]
	v_add_u32_e32 v148, 0xb0, v146
	v_ashrrev_i32_e32 v149, 31, v148
	v_lshlrev_b64 v[148:149], 12, v[148:149]
	v_lshl_add_u64 v[148:149], s[20:21], 0, v[148:149]
	v_lshl_add_u64 v[148:149], v[148:149], 0, v[144:145]
	global_load_dwordx4 v[180:183], v[148:149], off
	global_load_dwordx4 v[188:191], v[148:149], off offset:256
	global_load_dwordx4 v[216:219], v[148:149], off offset:2048
	global_load_dwordx4 v[220:223], v[148:149], off offset:2304
	s_waitcnt vmcnt(12)
	v_lshlrev_b32_e32 v224, 16, v192
	v_and_b32_e32 v225, 0xffff0000, v192
	v_lshlrev_b32_e32 v226, 16, v193
	v_and_b32_e32 v227, 0xffff0000, v193
	v_lshlrev_b32_e32 v228, 16, v194
	v_and_b32_e32 v229, 0xffff0000, v194
	v_lshlrev_b32_e32 v230, 16, v195
	v_and_b32_e32 v231, 0xffff0000, v195
	v_max_f32_e32 v224, 0x21800000, v224
	v_max_f32_e32 v225, 0x21800000, v225
	v_max_f32_e32 v226, 0x21800000, v226
	v_max_f32_e32 v227, 0x21800000, v227
	v_max_f32_e32 v228, 0x21800000, v228
	v_max_f32_e32 v229, 0x21800000, v229
	v_max_f32_e32 v230, 0x21800000, v230
	v_max_f32_e32 v231, 0x21800000, v231
	v_rcp_f32_e32 v224, v224
	v_rcp_f32_e32 v225, v225
	v_rcp_f32_e32 v226, v226
	v_rcp_f32_e32 v227, v227
	v_rcp_f32_e32 v228, v228
	v_rcp_f32_e32 v229, v229
	v_rcp_f32_e32 v230, v230
	v_rcp_f32_e32 v231, v231
	v_lshlrev_b32_e32 v232, 16, v156
	v_and_b32_e32 v233, 0xffff0000, v156
	v_lshlrev_b32_e32 v234, 16, v157
	v_and_b32_e32 v235, 0xffff0000, v157
	v_lshlrev_b32_e32 v236, 16, v158
	v_and_b32_e32 v237, 0xffff0000, v158
	v_lshlrev_b32_e32 v238, 16, v159
	v_and_b32_e32 v239, 0xffff0000, v159
	v_pk_mul_f32 v[232:233], v[232:233], v[224:225]
	v_pk_mul_f32 v[234:235], v[234:235], v[226:227]
	v_pk_mul_f32 v[236:237], v[236:237], v[228:229]
	v_pk_mul_f32 v[238:239], v[238:239], v[230:231]
	v_pk_mul_f32 v[60:61], v[60:61], v[232:233]
	v_pk_mul_f32 v[62:63], v[62:63], v[234:235]
	v_pk_mul_f32 v[52:53], v[52:53], v[236:237]
	v_pk_mul_f32 v[54:55], v[54:55], v[238:239]
	v_lshlrev_b32_e32 v224, 16, v196
	v_and_b32_e32 v225, 0xffff0000, v196
	v_lshlrev_b32_e32 v226, 16, v197
	v_and_b32_e32 v227, 0xffff0000, v197
	v_lshlrev_b32_e32 v228, 16, v198
	v_and_b32_e32 v229, 0xffff0000, v198
	v_lshlrev_b32_e32 v230, 16, v199
	v_and_b32_e32 v231, 0xffff0000, v199
	v_max_f32_e32 v224, 0x21800000, v224
	v_max_f32_e32 v225, 0x21800000, v225
	v_max_f32_e32 v226, 0x21800000, v226
	v_max_f32_e32 v227, 0x21800000, v227
	v_max_f32_e32 v228, 0x21800000, v228
	v_max_f32_e32 v229, 0x21800000, v229
	v_max_f32_e32 v230, 0x21800000, v230
	v_max_f32_e32 v231, 0x21800000, v231
	v_rcp_f32_e32 v224, v224
	v_rcp_f32_e32 v225, v225
	v_rcp_f32_e32 v226, v226
	v_rcp_f32_e32 v227, v227
	v_rcp_f32_e32 v228, v228
	v_rcp_f32_e32 v229, v229
	v_rcp_f32_e32 v230, v230
	v_rcp_f32_e32 v231, v231
	v_lshlrev_b32_e32 v232, 16, v160
	v_and_b32_e32 v233, 0xffff0000, v160
	v_lshlrev_b32_e32 v234, 16, v161
	v_and_b32_e32 v235, 0xffff0000, v161
	v_lshlrev_b32_e32 v236, 16, v162
	v_and_b32_e32 v237, 0xffff0000, v162
	v_lshlrev_b32_e32 v238, 16, v163
	v_and_b32_e32 v239, 0xffff0000, v163
	v_pk_mul_f32 v[232:233], v[232:233], v[224:225]
	v_pk_mul_f32 v[234:235], v[234:235], v[226:227]
	v_pk_mul_f32 v[236:237], v[236:237], v[228:229]
	v_pk_mul_f32 v[238:239], v[238:239], v[230:231]
	v_pk_mul_f32 v[56:57], v[56:57], v[232:233]
	v_pk_mul_f32 v[58:59], v[58:59], v[234:235]
	v_pk_mul_f32 v[48:49], v[48:49], v[236:237]
	v_pk_mul_f32 v[50:51], v[50:51], v[238:239]
	s_waitcnt vmcnt(8)
	v_lshlrev_b32_e32 v224, 16, v200
	v_and_b32_e32 v225, 0xffff0000, v200
	v_lshlrev_b32_e32 v226, 16, v201
	v_and_b32_e32 v227, 0xffff0000, v201
	v_lshlrev_b32_e32 v228, 16, v202
	v_and_b32_e32 v229, 0xffff0000, v202
	v_lshlrev_b32_e32 v230, 16, v203
	v_and_b32_e32 v231, 0xffff0000, v203
	v_max_f32_e32 v224, 0x21800000, v224
	v_max_f32_e32 v225, 0x21800000, v225
	v_max_f32_e32 v226, 0x21800000, v226
	v_max_f32_e32 v227, 0x21800000, v227
	v_max_f32_e32 v228, 0x21800000, v228
	v_max_f32_e32 v229, 0x21800000, v229
	v_max_f32_e32 v230, 0x21800000, v230
	v_max_f32_e32 v231, 0x21800000, v231
	v_rcp_f32_e32 v224, v224
	v_rcp_f32_e32 v225, v225
	v_rcp_f32_e32 v226, v226
	v_rcp_f32_e32 v227, v227
	v_rcp_f32_e32 v228, v228
	v_rcp_f32_e32 v229, v229
	v_rcp_f32_e32 v230, v230
	v_rcp_f32_e32 v231, v231
	v_lshlrev_b32_e32 v232, 16, v164
	v_and_b32_e32 v233, 0xffff0000, v164
	v_lshlrev_b32_e32 v234, 16, v165
	v_and_b32_e32 v235, 0xffff0000, v165
	v_lshlrev_b32_e32 v236, 16, v166
	v_and_b32_e32 v237, 0xffff0000, v166
	v_lshlrev_b32_e32 v238, 16, v167
	v_and_b32_e32 v239, 0xffff0000, v167
	v_pk_mul_f32 v[232:233], v[232:233], v[224:225]
	v_pk_mul_f32 v[234:235], v[234:235], v[226:227]
	v_pk_mul_f32 v[236:237], v[236:237], v[228:229]
	v_pk_mul_f32 v[238:239], v[238:239], v[230:231]
	v_pk_mul_f32 v[44:45], v[44:45], v[232:233]
	v_pk_mul_f32 v[46:47], v[46:47], v[234:235]
	v_pk_mul_f32 v[36:37], v[36:37], v[236:237]
	v_pk_mul_f32 v[38:39], v[38:39], v[238:239]
	v_lshlrev_b32_e32 v224, 16, v204
	v_and_b32_e32 v225, 0xffff0000, v204
	v_lshlrev_b32_e32 v226, 16, v205
	v_and_b32_e32 v227, 0xffff0000, v205
	v_lshlrev_b32_e32 v228, 16, v206
	v_and_b32_e32 v229, 0xffff0000, v206
	v_lshlrev_b32_e32 v230, 16, v207
	v_and_b32_e32 v231, 0xffff0000, v207
	v_max_f32_e32 v224, 0x21800000, v224
	v_max_f32_e32 v225, 0x21800000, v225
	v_max_f32_e32 v226, 0x21800000, v226
	v_max_f32_e32 v227, 0x21800000, v227
	v_max_f32_e32 v228, 0x21800000, v228
	v_max_f32_e32 v229, 0x21800000, v229
	v_max_f32_e32 v230, 0x21800000, v230
	v_max_f32_e32 v231, 0x21800000, v231
	v_rcp_f32_e32 v224, v224
	v_rcp_f32_e32 v225, v225
	v_rcp_f32_e32 v226, v226
	v_rcp_f32_e32 v227, v227
	v_rcp_f32_e32 v228, v228
	v_rcp_f32_e32 v229, v229
	v_rcp_f32_e32 v230, v230
	v_rcp_f32_e32 v231, v231
	v_lshlrev_b32_e32 v232, 16, v168
	v_and_b32_e32 v233, 0xffff0000, v168
	v_lshlrev_b32_e32 v234, 16, v169
	v_and_b32_e32 v235, 0xffff0000, v169
	v_lshlrev_b32_e32 v236, 16, v170
	v_and_b32_e32 v237, 0xffff0000, v170
	v_lshlrev_b32_e32 v238, 16, v171
	v_and_b32_e32 v239, 0xffff0000, v171
	v_pk_mul_f32 v[232:233], v[232:233], v[224:225]
	v_pk_mul_f32 v[234:235], v[234:235], v[226:227]
	v_pk_mul_f32 v[236:237], v[236:237], v[228:229]
	v_pk_mul_f32 v[238:239], v[238:239], v[230:231]
	v_pk_mul_f32 v[40:41], v[40:41], v[232:233]
	v_pk_mul_f32 v[42:43], v[42:43], v[234:235]
	v_pk_mul_f32 v[32:33], v[32:33], v[236:237]
	v_pk_mul_f32 v[34:35], v[34:35], v[238:239]
	s_waitcnt vmcnt(4)
	v_lshlrev_b32_e32 v224, 16, v208
	v_and_b32_e32 v225, 0xffff0000, v208
	v_lshlrev_b32_e32 v226, 16, v209
	v_and_b32_e32 v227, 0xffff0000, v209
	v_lshlrev_b32_e32 v228, 16, v210
	v_and_b32_e32 v229, 0xffff0000, v210
	v_lshlrev_b32_e32 v230, 16, v211
	v_and_b32_e32 v231, 0xffff0000, v211
	v_max_f32_e32 v224, 0x21800000, v224
	v_max_f32_e32 v225, 0x21800000, v225
	v_max_f32_e32 v226, 0x21800000, v226
	v_max_f32_e32 v227, 0x21800000, v227
	v_max_f32_e32 v228, 0x21800000, v228
	v_max_f32_e32 v229, 0x21800000, v229
	v_max_f32_e32 v230, 0x21800000, v230
	v_max_f32_e32 v231, 0x21800000, v231
	v_rcp_f32_e32 v224, v224
	v_rcp_f32_e32 v225, v225
	v_rcp_f32_e32 v226, v226
	v_rcp_f32_e32 v227, v227
	v_rcp_f32_e32 v228, v228
	v_rcp_f32_e32 v229, v229
	v_rcp_f32_e32 v230, v230
	v_rcp_f32_e32 v231, v231
	v_lshlrev_b32_e32 v232, 16, v172
	v_and_b32_e32 v233, 0xffff0000, v172
	v_lshlrev_b32_e32 v234, 16, v173
	v_and_b32_e32 v235, 0xffff0000, v173
	v_lshlrev_b32_e32 v236, 16, v174
	v_and_b32_e32 v237, 0xffff0000, v174
	v_lshlrev_b32_e32 v238, 16, v175
	v_and_b32_e32 v239, 0xffff0000, v175
	v_pk_mul_f32 v[232:233], v[232:233], v[224:225]
	v_pk_mul_f32 v[234:235], v[234:235], v[226:227]
	v_pk_mul_f32 v[236:237], v[236:237], v[228:229]
	v_pk_mul_f32 v[238:239], v[238:239], v[230:231]
	v_pk_mul_f32 v[28:29], v[28:29], v[232:233]
	v_pk_mul_f32 v[30:31], v[30:31], v[234:235]
	v_pk_mul_f32 v[20:21], v[20:21], v[236:237]
	v_pk_mul_f32 v[22:23], v[22:23], v[238:239]
	v_lshlrev_b32_e32 v224, 16, v212
	v_and_b32_e32 v225, 0xffff0000, v212
	v_lshlrev_b32_e32 v226, 16, v213
	v_and_b32_e32 v227, 0xffff0000, v213
	v_lshlrev_b32_e32 v228, 16, v214
	v_and_b32_e32 v229, 0xffff0000, v214
	v_lshlrev_b32_e32 v230, 16, v215
	v_and_b32_e32 v231, 0xffff0000, v215
	v_max_f32_e32 v224, 0x21800000, v224
	v_max_f32_e32 v225, 0x21800000, v225
	v_max_f32_e32 v226, 0x21800000, v226
	v_max_f32_e32 v227, 0x21800000, v227
	v_max_f32_e32 v228, 0x21800000, v228
	v_max_f32_e32 v229, 0x21800000, v229
	v_max_f32_e32 v230, 0x21800000, v230
	v_max_f32_e32 v231, 0x21800000, v231
	v_rcp_f32_e32 v224, v224
	v_rcp_f32_e32 v225, v225
	v_rcp_f32_e32 v226, v226
	v_rcp_f32_e32 v227, v227
	v_rcp_f32_e32 v228, v228
	v_rcp_f32_e32 v229, v229
	v_rcp_f32_e32 v230, v230
	v_rcp_f32_e32 v231, v231
	v_lshlrev_b32_e32 v232, 16, v176
	v_and_b32_e32 v233, 0xffff0000, v176
	v_lshlrev_b32_e32 v234, 16, v177
	v_and_b32_e32 v235, 0xffff0000, v177
	v_lshlrev_b32_e32 v236, 16, v178
	v_and_b32_e32 v237, 0xffff0000, v178
	v_lshlrev_b32_e32 v238, 16, v179
	v_and_b32_e32 v239, 0xffff0000, v179
	v_pk_mul_f32 v[232:233], v[232:233], v[224:225]
	v_pk_mul_f32 v[234:235], v[234:235], v[226:227]
	v_pk_mul_f32 v[236:237], v[236:237], v[228:229]
	v_pk_mul_f32 v[238:239], v[238:239], v[230:231]
	v_pk_mul_f32 v[24:25], v[24:25], v[232:233]
	v_pk_mul_f32 v[26:27], v[26:27], v[234:235]
	v_pk_mul_f32 v[16:17], v[16:17], v[236:237]
	v_pk_mul_f32 v[18:19], v[18:19], v[238:239]
	s_waitcnt vmcnt(0)
	v_lshlrev_b32_e32 v224, 16, v216
	v_and_b32_e32 v225, 0xffff0000, v216
	v_lshlrev_b32_e32 v226, 16, v217
	v_and_b32_e32 v227, 0xffff0000, v217
	v_lshlrev_b32_e32 v228, 16, v218
	v_and_b32_e32 v229, 0xffff0000, v218
	v_lshlrev_b32_e32 v230, 16, v219
	v_and_b32_e32 v231, 0xffff0000, v219
	v_max_f32_e32 v224, 0x21800000, v224
	v_max_f32_e32 v225, 0x21800000, v225
	v_max_f32_e32 v226, 0x21800000, v226
	v_max_f32_e32 v227, 0x21800000, v227
	v_max_f32_e32 v228, 0x21800000, v228
	v_max_f32_e32 v229, 0x21800000, v229
	v_max_f32_e32 v230, 0x21800000, v230
	v_max_f32_e32 v231, 0x21800000, v231
	v_rcp_f32_e32 v224, v224
	v_rcp_f32_e32 v225, v225
	v_rcp_f32_e32 v226, v226
	v_rcp_f32_e32 v227, v227
	v_rcp_f32_e32 v228, v228
	v_rcp_f32_e32 v229, v229
	v_rcp_f32_e32 v230, v230
	v_rcp_f32_e32 v231, v231
	v_lshlrev_b32_e32 v232, 16, v180
	v_and_b32_e32 v233, 0xffff0000, v180
	v_lshlrev_b32_e32 v234, 16, v181
	v_and_b32_e32 v235, 0xffff0000, v181
	v_lshlrev_b32_e32 v236, 16, v182
	v_and_b32_e32 v237, 0xffff0000, v182
	v_lshlrev_b32_e32 v238, 16, v183
	v_and_b32_e32 v239, 0xffff0000, v183
	v_pk_mul_f32 v[232:233], v[232:233], v[224:225]
	v_pk_mul_f32 v[234:235], v[234:235], v[226:227]
	v_pk_mul_f32 v[236:237], v[236:237], v[228:229]
	v_pk_mul_f32 v[238:239], v[238:239], v[230:231]
	v_pk_mul_f32 v[12:13], v[12:13], v[232:233]
	v_pk_mul_f32 v[14:15], v[14:15], v[234:235]
	v_pk_mul_f32 v[4:5], v[4:5], v[236:237]
	v_pk_mul_f32 v[6:7], v[6:7], v[238:239]
	v_lshlrev_b32_e32 v224, 16, v220
	v_and_b32_e32 v225, 0xffff0000, v220
	v_lshlrev_b32_e32 v226, 16, v221
	v_and_b32_e32 v227, 0xffff0000, v221
	v_lshlrev_b32_e32 v228, 16, v222
	v_and_b32_e32 v229, 0xffff0000, v222
	v_lshlrev_b32_e32 v230, 16, v223
	v_and_b32_e32 v231, 0xffff0000, v223
	v_max_f32_e32 v224, 0x21800000, v224
	v_max_f32_e32 v225, 0x21800000, v225
	v_max_f32_e32 v226, 0x21800000, v226
	v_max_f32_e32 v227, 0x21800000, v227
	v_max_f32_e32 v228, 0x21800000, v228
	v_max_f32_e32 v229, 0x21800000, v229
	v_max_f32_e32 v230, 0x21800000, v230
	v_max_f32_e32 v231, 0x21800000, v231
	v_rcp_f32_e32 v224, v224
	v_rcp_f32_e32 v225, v225
	v_rcp_f32_e32 v226, v226
	v_rcp_f32_e32 v227, v227
	v_rcp_f32_e32 v228, v228
	v_rcp_f32_e32 v229, v229
	v_rcp_f32_e32 v230, v230
	v_rcp_f32_e32 v231, v231
	v_lshlrev_b32_e32 v232, 16, v188
	v_and_b32_e32 v233, 0xffff0000, v188
	v_lshlrev_b32_e32 v234, 16, v189
	v_and_b32_e32 v235, 0xffff0000, v189
	v_lshlrev_b32_e32 v236, 16, v190
	v_and_b32_e32 v237, 0xffff0000, v190
	v_lshlrev_b32_e32 v238, 16, v191
	v_and_b32_e32 v239, 0xffff0000, v191
	v_pk_mul_f32 v[232:233], v[232:233], v[224:225]
	v_pk_mul_f32 v[234:235], v[234:235], v[226:227]
	v_pk_mul_f32 v[236:237], v[236:237], v[228:229]
	v_pk_mul_f32 v[238:239], v[238:239], v[230:231]
	v_pk_mul_f32 v[8:9], v[8:9], v[232:233]
	v_pk_mul_f32 v[10:11], v[10:11], v[234:235]
	v_pk_mul_f32 v[0:1], v[0:1], v[236:237]
	v_pk_mul_f32 v[2:3], v[2:3], v[238:239]
	s_andn2_b64 vcc, exec, s[16:17]
	s_cbranch_vccnz .LBB0_1053
	s_barrier
	s_branch .LBB0_1053
